# code placement: heads of the five large GEMM K loops at 32 mod 64 bytes
# speedup vs baseline: 1.0014x; 1.0014x over previous
; template <class Epi, class Sched>
; __device__ __forceinline__ void gemm_phase(LAS unsigned char* lds, const Gemm g, const Sched& S, const Epi& E) {
;     ...
;     for (;;) {
;         const bool has_next = S.next(ui + 1, nxt);
;         const char* nA = has_next ? (const char*)g.A + (size_t)nxt.pm * tA + (size_t)nxt.k0 * 2 : cA; const char* nB = has_next ? (const char*)g.Bt + (size_t)nxt.pn * tB + (size_t)nxt.k0 * 2 : cB;
;         const int nt = cur.nt;
;         for (int t = 0; t < nt; t += 2) {
;     ...
;             bf16x8 zf = {0, 0, 0, 0, 0, 0, 0, 0}; asm volatile("" : "+v"(zf));
; #pragma unroll
;             for (int a = 0; a < 2; ++a)
; #pragma unroll
;                 for (int b = 0; b < 2; ++b)
; #pragma unroll
;                     for (int m = 0; m < 4; ++m)
; #pragma unroll
;                         for (int n = 0; n < 2; ++n) acc[a][b][m][n] = __builtin_amdgcn_mfma_f32_16x16x32_bf16(zf, zf, (f32x4){0.f, 0.f, 0.f, 0.f}, 0, 0, 0);
.LBB0_258:
	s_ashr_i32 s17, s16, 31
	s_lshl_b64 s[18:19], s[16:17], 20
	v_readlane_b32 s20, v253, 34
	v_readlane_b32 s21, v253, 35
	s_add_u32 s18, s20, s18
	s_addc_u32 s19, s21, s19
	s_and_b64 s[20:21], s[0:1], exec
	s_cselect_b32 s17, s19, s3
	s_cselect_b32 s26, s18, s2
	s_ashr_i32 s15, s14, 31
	s_lshl_b64 s[20:21], s[14:15], 20
	s_add_u32 s20, s30, s20
	s_addc_u32 s21, s31, s21
	s_and_b64 s[24:25], s[0:1], exec
	s_cselect_b32 s15, s21, s23
	s_cselect_b32 s27, s20, s22
	s_add_u32 s2, s2, 0x80080
	s_addc_u32 s3, s3, 0
	s_add_u32 s28, s22, 0x100
	s_waitcnt vmcnt(12)
	v_mov_b64_e32 v[2:3], v[206:207]
	v_mov_b64_e32 v[4:5], v[208:209]
	v_mov_b64_e32 v[6:7], v[202:203]
	v_mov_b64_e32 v[8:9], v[204:205]
	v_mov_b64_e32 v[10:11], v[198:199]
	v_mov_b64_e32 v[12:13], v[200:201]
	v_mov_b64_e32 v[14:15], v[194:195]
	v_mov_b64_e32 v[16:17], v[196:197]
	v_mov_b64_e32 v[18:19], v[206:207]
	v_mov_b64_e32 v[20:21], v[208:209]
	v_mov_b64_e32 v[22:23], v[202:203]
	v_mov_b64_e32 v[24:25], v[204:205]
	v_mov_b64_e32 v[26:27], v[198:199]
	v_mov_b64_e32 v[28:29], v[200:201]
	v_mov_b64_e32 v[30:31], v[194:195]
	v_mov_b64_e32 v[32:33], v[196:197]
	v_mov_b64_e32 v[34:35], v[206:207]
	v_mov_b64_e32 v[36:37], v[208:209]
	v_mov_b64_e32 v[38:39], v[202:203]
	v_mov_b64_e32 v[40:41], v[204:205]
	v_mov_b64_e32 v[50:51], v[198:199]
	v_mov_b64_e32 v[52:53], v[200:201]
	v_mov_b64_e32 v[54:55], v[194:195]
	v_mov_b64_e32 v[56:57], v[196:197]
	v_mov_b64_e32 v[66:67], v[206:207]
	v_mov_b64_e32 v[68:69], v[208:209]
	v_mov_b64_e32 v[70:71], v[202:203]
	v_mov_b64_e32 v[72:73], v[204:205]
	v_mov_b64_e32 v[74:75], v[198:199]
	v_mov_b64_e32 v[76:77], v[200:201]
	v_mov_b64_e32 v[78:79], v[194:195]
	v_mov_b64_e32 v[80:81], v[196:197]
	v_mov_b64_e32 v[82:83], v[206:207]
	v_mov_b64_e32 v[84:85], v[208:209]
	v_mov_b64_e32 v[86:87], v[202:203]
	v_mov_b64_e32 v[88:89], v[204:205]
	v_mov_b64_e32 v[90:91], v[198:199]
	v_mov_b64_e32 v[92:93], v[200:201]
	v_mov_b64_e32 v[94:95], v[194:195]
	v_mov_b64_e32 v[96:97], v[196:197]
	v_mov_b64_e32 v[100:101], v[206:207]
	v_mov_b64_e32 v[102:103], v[208:209]
	v_mov_b64_e32 v[104:105], v[202:203]
	v_mov_b64_e32 v[106:107], v[204:205]
	v_mov_b64_e32 v[108:109], v[198:199]
	v_mov_b64_e32 v[110:111], v[200:201]
	v_mov_b64_e32 v[112:113], v[194:195]
	v_mov_b64_e32 v[114:115], v[196:197]
	v_mov_b64_e32 v[116:117], v[206:207]
	v_mov_b64_e32 v[118:119], v[208:209]
	v_mov_b64_e32 v[120:121], v[202:203]
	v_mov_b64_e32 v[122:123], v[204:205]
	v_mov_b64_e32 v[124:125], v[198:199]
	v_mov_b64_e32 v[126:127], v[200:201]
	v_mov_b64_e32 v[128:129], v[194:195]
	v_mov_b64_e32 v[130:131], v[196:197]
	v_mov_b64_e32 v[132:133], v[206:207]
	v_mov_b64_e32 v[134:135], v[208:209]
	v_mov_b64_e32 v[136:137], v[202:203]
	v_mov_b64_e32 v[138:139], v[204:205]
	v_mov_b64_e32 v[140:141], v[198:199]
	v_mov_b64_e32 v[142:143], v[200:201]
	v_mov_b64_e32 v[144:145], v[194:195]
	v_mov_b64_e32 v[146:147], v[196:197]
	s_addc_u32 s29, s23, 0
	s_mov_b32 s46, -2
	.p2alignl 6, 3212836864
	s_nop 0
	s_nop 0
	s_nop 0
	s_nop 0
	s_nop 0
	s_nop 0
	s_nop 0
	s_nop 0

; template <class Epi, class Sched>
; __device__ __forceinline__ void gemm_phase(LAS unsigned char* lds, const Gemm g, const Sched& S, const Epi& E) {
;     ...
;     for (;;) {
;         const bool has_next = S.next(ui + 1, nxt);
;         const char* nA = has_next ? (const char*)g.A + (size_t)nxt.pm * tA + (size_t)nxt.k0 * 2 : cA; const char* nB = has_next ? (const char*)g.Bt + (size_t)nxt.pn * tB + (size_t)nxt.k0 * 2 : cB;
;         const int nt = cur.nt;
;         for (int t = 0; t < nt; t += 2) {
;             const bool last = (t == nt - 2);
;             const char* a1 = cA + (size_t)(t + 1) * kstepA;
;             const char* a2 = last ? nA : cA + (size_t)(t + 2) * kstepA; const char* b2 = last ? nB : cB + (size_t)(t + 2) * kstep;
;             const char* a3 = a2 + kstepA; const char* b3 = b2 + kstep;
.LBB0_707:
	s_ashr_i32 s13, s12, 31
	s_lshl_b64 s[16:17], s[12:13], 20
	s_add_u32 s9, s33, s16
	s_addc_u32 s13, s54, s17
	s_ashr_i32 s15, s14, 31
	s_lshl_b64 s[18:19], s[14:15], 1
	s_add_u32 s16, s9, s18
	s_addc_u32 s17, s13, s19
	s_and_b64 s[22:23], s[0:1], exec
	s_cselect_b32 s13, s17, s3
	s_cselect_b32 s15, s16, s2
	s_ashr_i32 s9, s8, 31
	s_lshl_b64 s[22:23], s[8:9], 20
	s_add_u32 s9, s26, s22
	s_addc_u32 s22, s27, s23
	s_add_u32 s18, s9, s18
	s_addc_u32 s19, s22, s19
	s_and_b64 s[22:23], s[0:1], exec
	s_cselect_b32 s9, s19, s21
	s_cselect_b32 s42, s18, s20
	s_add_i32 s43, s24, -2
	s_add_u32 s2, s2, 0x80080
	s_addc_u32 s3, s3, 0
	s_add_u32 s46, s20, 0x100
	s_addc_u32 s47, s21, 0
	s_mov_b32 s20, 0
	.p2alignl 6, 3212836864
	s_nop 0
	s_nop 0
	s_nop 0
	s_nop 0
	s_nop 0
	s_nop 0
	s_nop 0
	s_nop 0

; template <class Epi, class Sched>
; __device__ __forceinline__ void gemm_phase(LAS unsigned char* lds, const Gemm g, const Sched& S, const Epi& E) {
;     ...
;     for (;;) {
;         const bool has_next = S.next(ui + 1, nxt);
;         const char* nA = has_next ? (const char*)g.A + (size_t)nxt.pm * tA + (size_t)nxt.k0 * 2 : cA; const char* nB = has_next ? (const char*)g.Bt + (size_t)nxt.pn * tB + (size_t)nxt.k0 * 2 : cB;
;         const int nt = cur.nt;
;         for (int t = 0; t < nt; t += 2) {
;     ...
;             bf16x8 zf = {0, 0, 0, 0, 0, 0, 0, 0}; asm volatile("" : "+v"(zf));
; #pragma unroll
;             for (int a = 0; a < 2; ++a)
; #pragma unroll
;                 for (int b = 0; b < 2; ++b)
; #pragma unroll
;                     for (int m = 0; m < 4; ++m)
; #pragma unroll
;                         for (int n = 0; n < 2; ++n) acc[a][b][m][n] = __builtin_amdgcn_mfma_f32_16x16x32_bf16(zf, zf, (f32x4){0.f, 0.f, 0.f, 0.f}, 0, 0, 0);
.LBB0_841:
	s_ashr_i32 s19, s18, 31
	s_lshl_b64 s[20:21], s[18:19], 20
	v_readlane_b32 s22, v253, 34
	v_readlane_b32 s23, v253, 35
	s_add_u32 s20, s22, s20
	s_addc_u32 s21, s23, s21
	s_and_b64 s[22:23], s[74:75], exec
	s_cselect_b32 s19, s21, s25
	s_cselect_b32 s46, s20, s24
	s_ashr_i32 s17, s16, 31
	s_lshl_b64 s[22:23], s[16:17], 20
	s_add_u32 s22, s30, s22
	s_addc_u32 s23, s31, s23
	s_and_b64 s[26:27], s[74:75], exec
	s_cselect_b32 s17, s23, s3
	s_cselect_b32 s47, s22, s2
	s_add_u32 s48, s2, 0x100
	v_mov_b64_e32 v[8:9], v[4:5]
	v_mov_b64_e32 v[20:21], v[4:5]
	v_mov_b64_e32 v[24:25], v[4:5]
	v_mov_b64_e32 v[36:37], v[4:5]
	v_mov_b64_e32 v[40:41], v[4:5]
	v_mov_b64_e32 v[52:53], v[4:5]
	v_mov_b64_e32 v[56:57], v[4:5]
	v_mov_b64_e32 v[12:13], v[4:5]
	v_mov_b64_e32 v[16:17], v[4:5]
	v_mov_b64_e32 v[28:29], v[4:5]
	v_mov_b64_e32 v[32:33], v[4:5]
	v_mov_b64_e32 v[44:45], v[4:5]
	v_mov_b64_e32 v[48:49], v[4:5]
	v_mov_b64_e32 v[60:61], v[4:5]
	v_mov_b64_e32 v[64:65], v[4:5]
	v_mov_b64_e32 v[68:69], v[4:5]
	v_mov_b64_e32 v[72:73], v[4:5]
	v_mov_b64_e32 v[84:85], v[4:5]
	v_mov_b64_e32 v[88:89], v[4:5]
	v_mov_b64_e32 v[102:103], v[4:5]
	v_mov_b64_e32 v[106:107], v[4:5]
	v_mov_b64_e32 v[118:119], v[4:5]
	v_mov_b64_e32 v[122:123], v[4:5]
	v_mov_b64_e32 v[76:77], v[4:5]
	v_mov_b64_e32 v[80:81], v[4:5]
	v_mov_b64_e32 v[92:93], v[4:5]
	v_mov_b64_e32 v[96:97], v[4:5]
	v_mov_b64_e32 v[110:111], v[4:5]
	v_mov_b64_e32 v[114:115], v[4:5]
	v_mov_b64_e32 v[126:127], v[4:5]
	v_mov_b64_e32 v[130:131], v[4:5]
	s_addc_u32 s50, s3, 0
	s_mov_b32 s52, -2
	v_mov_b64_e32 v[6:7], v[2:3]
	v_mov_b64_e32 v[18:19], v[2:3]
	v_mov_b64_e32 v[22:23], v[2:3]
	v_mov_b64_e32 v[34:35], v[2:3]
	v_mov_b64_e32 v[38:39], v[2:3]
	v_mov_b64_e32 v[50:51], v[2:3]
	v_mov_b64_e32 v[54:55], v[2:3]
	v_mov_b64_e32 v[10:11], v[2:3]
	v_mov_b64_e32 v[14:15], v[2:3]
	v_mov_b64_e32 v[26:27], v[2:3]
	v_mov_b64_e32 v[30:31], v[2:3]
	v_mov_b64_e32 v[42:43], v[2:3]
	v_mov_b64_e32 v[46:47], v[2:3]
	v_mov_b64_e32 v[58:59], v[2:3]
	v_mov_b64_e32 v[62:63], v[2:3]
	v_mov_b64_e32 v[66:67], v[2:3]
	v_mov_b64_e32 v[70:71], v[2:3]
	v_mov_b64_e32 v[82:83], v[2:3]
	v_mov_b64_e32 v[86:87], v[2:3]
	v_mov_b64_e32 v[100:101], v[2:3]
	v_mov_b64_e32 v[104:105], v[2:3]
	v_mov_b64_e32 v[116:117], v[2:3]
	v_mov_b64_e32 v[120:121], v[2:3]
	v_mov_b64_e32 v[74:75], v[2:3]
	v_mov_b64_e32 v[78:79], v[2:3]
	v_mov_b64_e32 v[90:91], v[2:3]
	v_mov_b64_e32 v[94:95], v[2:3]
	v_mov_b64_e32 v[108:109], v[2:3]
	v_mov_b64_e32 v[112:113], v[2:3]
	v_mov_b64_e32 v[124:125], v[2:3]
	v_mov_b64_e32 v[128:129], v[2:3]
	s_mov_b64 s[96:97], 0x100
	.p2alignl 6, 3212836864
	s_nop 0
	s_nop 0
	s_nop 0
	s_nop 0
	s_nop 0
	s_nop 0
	s_nop 0
	s_nop 0

; template <class Epi, class Sched>
; __device__ __forceinline__ void gemm_phase(LAS unsigned char* lds, const Gemm g, const Sched& S, const Epi& E) {
;     ...
;     for (;;) {
;         const bool has_next = S.next(ui + 1, nxt);
;         const char* nA = has_next ? (const char*)g.A + (size_t)nxt.pm * tA + (size_t)nxt.k0 * 2 : cA; const char* nB = has_next ? (const char*)g.Bt + (size_t)nxt.pn * tB + (size_t)nxt.k0 * 2 : cB;
;         const int nt = cur.nt;
;         for (int t = 0; t < nt; t += 2) {
;     ...
;             bf16x8 zf = {0, 0, 0, 0, 0, 0, 0, 0}; asm volatile("" : "+v"(zf));
; #pragma unroll
;             for (int a = 0; a < 2; ++a)
; #pragma unroll
;                 for (int b = 0; b < 2; ++b)
; #pragma unroll
;                     for (int m = 0; m < 4; ++m)
; #pragma unroll
;                         for (int n = 0; n < 2; ++n) acc[a][b][m][n] = __builtin_amdgcn_mfma_f32_16x16x32_bf16(zf, zf, (f32x4){0.f, 0.f, 0.f, 0.f}, 0, 0, 0);
.LBB0_977:
	s_ashr_i32 s9, s8, 31
	s_lshl_b64 s[12:13], s[8:9], 20
	v_readlane_b32 s14, v253, 34
	v_readlane_b32 s15, v253, 35
	s_add_u32 s12, s14, s12
	s_addc_u32 s13, s15, s13
	s_and_b64 s[14:15], s[0:1], exec
	s_cselect_b32 s9, s13, s17
	s_cselect_b32 s36, s12, s16
	s_ashr_i32 s7, s6, 31
	s_lshl_b64 s[14:15], s[6:7], 20
	s_add_u32 s14, s22, s14
	s_addc_u32 s15, s23, s15
	s_and_b64 s[20:21], s[0:1], exec
	s_cselect_b32 s7, s15, s19
	s_cselect_b32 s37, s14, s18
	s_add_u32 s16, s16, 0x80080
	s_addc_u32 s17, s17, 0
	s_add_u32 s38, s18, 0x100
	v_mov_b64_e32 v[8:9], v[4:5]
	v_mov_b64_e32 v[20:21], v[4:5]
	v_mov_b64_e32 v[24:25], v[4:5]
	v_mov_b64_e32 v[36:37], v[4:5]
	v_mov_b64_e32 v[40:41], v[4:5]
	v_mov_b64_e32 v[52:53], v[4:5]
	v_mov_b64_e32 v[56:57], v[4:5]
	v_mov_b64_e32 v[12:13], v[4:5]
	v_mov_b64_e32 v[16:17], v[4:5]
	v_mov_b64_e32 v[28:29], v[4:5]
	v_mov_b64_e32 v[32:33], v[4:5]
	v_mov_b64_e32 v[44:45], v[4:5]
	v_mov_b64_e32 v[48:49], v[4:5]
	v_mov_b64_e32 v[60:61], v[4:5]
	v_mov_b64_e32 v[64:65], v[4:5]
	v_mov_b64_e32 v[68:69], v[4:5]
	v_mov_b64_e32 v[72:73], v[4:5]
	v_mov_b64_e32 v[84:85], v[4:5]
	v_mov_b64_e32 v[88:89], v[4:5]
	v_mov_b64_e32 v[102:103], v[4:5]
	v_mov_b64_e32 v[106:107], v[4:5]
	v_mov_b64_e32 v[118:119], v[4:5]
	v_mov_b64_e32 v[122:123], v[4:5]
	v_mov_b64_e32 v[76:77], v[4:5]
	v_mov_b64_e32 v[80:81], v[4:5]
	v_mov_b64_e32 v[92:93], v[4:5]
	v_mov_b64_e32 v[96:97], v[4:5]
	v_mov_b64_e32 v[110:111], v[4:5]
	v_mov_b64_e32 v[114:115], v[4:5]
	v_mov_b64_e32 v[126:127], v[4:5]
	v_mov_b64_e32 v[130:131], v[4:5]
	s_addc_u32 s39, s19, 0
	s_mov_b32 s40, -2
	v_mov_b64_e32 v[6:7], v[2:3]
	v_mov_b64_e32 v[18:19], v[2:3]
	v_mov_b64_e32 v[22:23], v[2:3]
	v_mov_b64_e32 v[34:35], v[2:3]
	v_mov_b64_e32 v[38:39], v[2:3]
	v_mov_b64_e32 v[50:51], v[2:3]
	v_mov_b64_e32 v[54:55], v[2:3]
	v_mov_b64_e32 v[10:11], v[2:3]
	v_mov_b64_e32 v[14:15], v[2:3]
	v_mov_b64_e32 v[26:27], v[2:3]
	v_mov_b64_e32 v[30:31], v[2:3]
	v_mov_b64_e32 v[42:43], v[2:3]
	v_mov_b64_e32 v[46:47], v[2:3]
	v_mov_b64_e32 v[58:59], v[2:3]
	v_mov_b64_e32 v[62:63], v[2:3]
	v_mov_b64_e32 v[66:67], v[2:3]
	v_mov_b64_e32 v[70:71], v[2:3]
	v_mov_b64_e32 v[82:83], v[2:3]
	v_mov_b64_e32 v[86:87], v[2:3]
	v_mov_b64_e32 v[100:101], v[2:3]
	v_mov_b64_e32 v[104:105], v[2:3]
	v_mov_b64_e32 v[116:117], v[2:3]
	v_mov_b64_e32 v[120:121], v[2:3]
	v_mov_b64_e32 v[74:75], v[2:3]
	v_mov_b64_e32 v[78:79], v[2:3]
	v_mov_b64_e32 v[90:91], v[2:3]
	v_mov_b64_e32 v[94:95], v[2:3]
	v_mov_b64_e32 v[108:109], v[2:3]
	v_mov_b64_e32 v[112:113], v[2:3]
	v_mov_b64_e32 v[124:125], v[2:3]
	v_mov_b64_e32 v[128:129], v[2:3]
	.p2alignl 6, 3212836864
	s_nop 0
	s_nop 0
	s_nop 0
	s_nop 0
	s_nop 0
	s_nop 0
	s_nop 0
	s_nop 0

; template <class Epi, class Sched>
; __device__ __forceinline__ void gemm_phase(LAS unsigned char* lds, const Gemm g, const Sched& S, const Epi& E) {
;     ...
;     for (;;) {
;         const bool has_next = S.next(ui + 1, nxt);
;         const char* nA = has_next ? (const char*)g.A + (size_t)nxt.pm * tA + (size_t)nxt.k0 * 2 : cA; const char* nB = has_next ? (const char*)g.Bt + (size_t)nxt.pn * tB + (size_t)nxt.k0 * 2 : cB;
;         const int nt = cur.nt;
;         for (int t = 0; t < nt; t += 2) {
;     ...
;             bf16x8 zf = {0, 0, 0, 0, 0, 0, 0, 0}; asm volatile("" : "+v"(zf));
; #pragma unroll
;             for (int a = 0; a < 2; ++a)
; #pragma unroll
;                 for (int b = 0; b < 2; ++b)
; #pragma unroll
;                     for (int m = 0; m < 4; ++m)
; #pragma unroll
;                         for (int n = 0; n < 2; ++n) acc[a][b][m][n] = __builtin_amdgcn_mfma_f32_16x16x32_bf16(zf, zf, (f32x4){0.f, 0.f, 0.f, 0.f}, 0, 0, 0);
.LBB0_1047:
	s_add_u32 s42, s2, 0x100
	v_mov_b64_e32 v[8:9], v[4:5]
	v_mov_b64_e32 v[20:21], v[4:5]
	v_mov_b64_e32 v[24:25], v[4:5]
	v_mov_b64_e32 v[36:37], v[4:5]
	v_mov_b64_e32 v[40:41], v[4:5]
	v_mov_b64_e32 v[52:53], v[4:5]
	v_mov_b64_e32 v[56:57], v[4:5]
	v_mov_b64_e32 v[12:13], v[4:5]
	v_mov_b64_e32 v[16:17], v[4:5]
	v_mov_b64_e32 v[28:29], v[4:5]
	v_mov_b64_e32 v[32:33], v[4:5]
	v_mov_b64_e32 v[44:45], v[4:5]
	v_mov_b64_e32 v[48:49], v[4:5]
	v_mov_b64_e32 v[60:61], v[4:5]
	v_mov_b64_e32 v[64:65], v[4:5]
	v_mov_b64_e32 v[68:69], v[4:5]
	v_mov_b64_e32 v[72:73], v[4:5]
	v_mov_b64_e32 v[84:85], v[4:5]
	v_mov_b64_e32 v[88:89], v[4:5]
	v_mov_b64_e32 v[102:103], v[4:5]
	v_mov_b64_e32 v[106:107], v[4:5]
	v_mov_b64_e32 v[118:119], v[4:5]
	v_mov_b64_e32 v[122:123], v[4:5]
	v_mov_b64_e32 v[76:77], v[4:5]
	v_mov_b64_e32 v[80:81], v[4:5]
	v_mov_b64_e32 v[92:93], v[4:5]
	v_mov_b64_e32 v[96:97], v[4:5]
	v_mov_b64_e32 v[110:111], v[4:5]
	v_mov_b64_e32 v[114:115], v[4:5]
	v_mov_b64_e32 v[126:127], v[4:5]
	v_mov_b64_e32 v[130:131], v[4:5]
	s_addc_u32 s43, s3, 0
	s_mov_b32 s46, -2
	v_mov_b64_e32 v[6:7], v[2:3]
	v_mov_b64_e32 v[18:19], v[2:3]
	v_mov_b64_e32 v[22:23], v[2:3]
	v_mov_b64_e32 v[34:35], v[2:3]
	v_mov_b64_e32 v[38:39], v[2:3]
	v_mov_b64_e32 v[50:51], v[2:3]
	v_mov_b64_e32 v[54:55], v[2:3]
	v_mov_b64_e32 v[10:11], v[2:3]
	v_mov_b64_e32 v[14:15], v[2:3]
	v_mov_b64_e32 v[26:27], v[2:3]
	v_mov_b64_e32 v[30:31], v[2:3]
	v_mov_b64_e32 v[42:43], v[2:3]
	v_mov_b64_e32 v[46:47], v[2:3]
	v_mov_b64_e32 v[58:59], v[2:3]
	v_mov_b64_e32 v[62:63], v[2:3]
	v_mov_b64_e32 v[66:67], v[2:3]
	v_mov_b64_e32 v[70:71], v[2:3]
	v_mov_b64_e32 v[82:83], v[2:3]
	v_mov_b64_e32 v[86:87], v[2:3]
	v_mov_b64_e32 v[100:101], v[2:3]
	v_mov_b64_e32 v[104:105], v[2:3]
	v_mov_b64_e32 v[116:117], v[2:3]
	v_mov_b64_e32 v[120:121], v[2:3]
	v_mov_b64_e32 v[74:75], v[2:3]
	v_mov_b64_e32 v[78:79], v[2:3]
	v_mov_b64_e32 v[90:91], v[2:3]
	v_mov_b64_e32 v[94:95], v[2:3]
	v_mov_b64_e32 v[108:109], v[2:3]
	v_mov_b64_e32 v[112:113], v[2:3]
	v_mov_b64_e32 v[124:125], v[2:3]
	v_mov_b64_e32 v[128:129], v[2:3]
	.p2alignl 6, 3212836864
	s_nop 0
	s_nop 0
	s_nop 0
	s_nop 0
	s_nop 0
	s_nop 0
	s_nop 0
	s_nop 0
